# stack8 + P2: even-XCD three-tile workgroups take their tiles in reverse order (k tiles with the f32 cache stores first)
# speedup vs baseline: 1.0028x; 1.0016x over previous
.LBB0_157:
	v_writelane_b32 v255, s92, 13
	v_writelane_b32 v255, s86, 14
	s_cmp_lt_i32 s54, 3
	s_cselect_b64 s[40:41], -1, 0
	v_writelane_b32 v255, s87, 15
	v_writelane_b32 v255, s88, 16
	s_add_u32 s60, s18, 0x6000000
	s_addc_u32 s61, s19, 0
	v_writelane_b32 v255, s89, 17
	v_writelane_b32 v255, s94, 18
	s_add_u32 s52, s18, 0x9400000
	s_addc_u32 s53, s19, 0
	v_writelane_b32 v255, s95, 19
	v_writelane_b32 v255, s90, 20
	s_and_b64 s[0:1], s[40:41], s[6:7]
	s_andn2_b64 vcc, exec, s[0:1]
	v_writelane_b32 v255, s91, 21
	v_writelane_b32 v255, s54, 22
	v_writelane_b32 v255, s55, 23
	v_writelane_b32 v255, s96, 24
	s_nop 1
	v_writelane_b32 v255, s97, 25
	s_cbranch_vccnz .LBB0_465
	s_cmpk_lt_i32 s92, 0x280
	s_mov_b64 s[4:5], s[90:91]
	s_mov_b64 s[6:7], s[90:91]
	s_cselect_b64 s[42:43], -1, 0
	s_cmpk_gt_i32 s92, 0x27f
	v_readfirstlane_b32 s0, v0
	s_cbranch_scc1 .LBB0_160
	s_and_b32 s99, s92, 0x81
	s_cmp_eq_u32 s99, 0
	s_cselect_b32 s98, 0x200, 0
	s_add_i32 s98, s98, s92
	s_ashr_i32 s1, s98, 31
	s_lshr_b32 s1, s1, 29
	s_add_i32 s1, s98, s1
	s_ashr_i32 s2, s1, 3
	s_and_b32 s1, s1, -8
	s_sub_i32 s1, s98, s1
	s_cmp_lt_i32 s1, 0
	s_movk_i32 s3, 0x51
	s_cselect_b32 s3, s3, 0x50
	s_mul_i32 s1, s1, s3
	s_add_i32 s1, s1, s2
	s_mul_hi_i32 s2, s1, 0x66666667
	s_lshr_b32 s3, s2, 31
	s_ashr_i32 s2, s2, 6
	s_add_i32 s2, s2, s3
	s_lshl_b32 s3, s2, 3
	s_mulk_i32 s2, 0xa0
	s_sub_i32 s1, s1, s2
	s_sext_i32_i16 s2, s1
	s_bfe_u32 s2, s2, 0x3001c
	s_add_i32 s2, s1, s2
	s_sext_i32_i16 s8, s2
	s_and_b32 s2, s2, 0xfff8
	s_sub_i32 s1, s1, s2
	s_sext_i32_i16 s1, s1
	s_add_i32 s2, s3, s1
	s_ashr_i32 s20, s8, 3
	s_lshl_b32 s8, s2, 1
	s_ashr_i32 s9, s8, 31
	s_lshl_b64 s[8:9], s[8:9], 19
	s_add_u32 s10, s62, s8
	s_addc_u32 s11, s63, s9
	s_add_u32 s8, s10, 0x80000
	s_addc_u32 s9, s11, 0
	s_lshl_b32 s12, s20, 1
	s_ashr_i32 s13, s12, 31
	s_lshl_b64 s[12:13], s[12:13], 19
	s_add_u32 s84, s36, s12
	s_addc_u32 s85, s37, s13
	s_add_u32 s12, s84, 0x80000
	s_addc_u32 s13, s85, 0
	s_andn2_b64 vcc, exec, s[42:43]
	s_cbranch_vccz .LBB0_161
	s_branch .LBB0_431

.LBB0_166:
	v_readlane_b32 s6, v255, 20
	v_readlane_b32 s7, v255, 21
	s_load_dword s7, s[6:7], 0xe0
	s_add_i32 s48, s48, 1
	s_sub_i32 s98, 2, s48
	s_cmp_gt_u32 s48, 2
	s_cselect_b32 s98, s48, s98
	s_and_b32 s99, s92, 0x81
	s_cmp_eq_u32 s99, 0
	s_cselect_b32 s98, s98, s48
	s_mul_i32 s3, s98, s94
	s_waitcnt lgkmcnt(0)
	s_mul_hi_u32 s6, s98, s7
	s_add_i32 s6, s6, s3
	s_mul_i32 s3, s98, s7
	s_add_u32 s86, s3, s92
	s_addc_u32 s87, s6, s95
	v_cmp_gt_i64_e32 vcc, s[86:87], v[152:153]
	v_cmp_lt_i64_e64 s[6:7], s[86:87], v[150:151]
	s_cbranch_vccnz .LBB0_168
	s_ashr_i32 s3, s86, 31
	s_lshr_b32 s3, s3, 29
	s_add_i32 s3, s86, s3
	s_ashr_i32 s21, s3, 3
	s_and_b32 s3, s3, -8
	s_sub_i32 s3, s86, s3
	s_cmp_lt_i32 s3, 0
	s_movk_i32 s35, 0x51
	s_cselect_b32 s35, s35, 0x50
	s_mul_i32 s3, s3, s35
	s_add_i32 s3, s3, s21
	s_mul_hi_i32 s21, s3, 0x66666667
	s_lshr_b32 s35, s21, 31
	s_ashr_i32 s21, s21, 6
	s_add_i32 s21, s21, s35
	s_lshl_b32 s35, s21, 3
	s_sub_i32 s40, 32, s35
	s_min_i32 s40, s40, 8
	s_abs_i32 s49, s40
	v_cvt_f32_u32_e32 v2, s49
	s_sub_i32 s76, 0, s49
	s_mulk_i32 s21, 0xa0
	s_sub_i32 s3, s3, s21
	v_rcp_iflag_f32_e32 v2, v2
	s_abs_i32 s21, s3
	s_xor_b32 s50, s3, s40
	s_ashr_i32 s50, s50, 31
	v_mul_f32_e32 v2, 0x4f7ffffe, v2
	v_cvt_u32_f32_e32 v2, v2
	s_nop 0
	v_readfirstlane_b32 s77, v2
	s_mul_i32 s76, s76, s77
	s_mul_hi_u32 s76, s77, s76
	s_add_i32 s77, s77, s76
	s_mul_hi_u32 s76, s21, s77
	s_mul_i32 s77, s76, s49
	s_sub_i32 s21, s21, s77
	s_add_i32 s78, s76, 1
	s_sub_i32 s77, s21, s49
	s_cmp_ge_u32 s21, s49
	s_cselect_b32 s76, s78, s76
	s_cselect_b32 s21, s77, s21
	s_add_i32 s77, s76, 1
	s_cmp_ge_u32 s21, s49
	s_cselect_b32 s21, s77, s76
	s_xor_b32 s21, s21, s50
	s_sub_i32 s49, s21, s50
	s_mul_i32 s21, s49, s40
	s_sub_i32 s3, s3, s21
	s_add_i32 s35, s35, s3
	s_cmp_lg_u32 s48, 1
	s_cbranch_scc1 .Lp2_noswap
	s_cmp_lt_i32 s49, 10
	s_cselect_b32 s3, 10, -10
	s_add_i32 s49, s49, s3
